# 16x16x32-layout attention unit with XOR-swizzled LDS exchange in the epilogue and early sub-LN gain loads
# speedup vs baseline: 1.0106x; 1.0106x over previous
.La16_fin:
	v_lshlrev_b32_e32 v216, 1, v160
	global_load_dwordx4 v[64:67], v216, s[56:57]
	global_load_dwordx4 v[68:71], v216, s[56:57] offset:16
	global_load_dwordx4 v[72:75], v216, s[56:57] offset:32
	global_load_dwordx4 v[76:79], v216, s[56:57] offset:48
	global_load_dwordx4 v[80:83], v216, s[56:57] offset:64
	global_load_dwordx4 v[84:87], v216, s[56:57] offset:80
	global_load_dwordx4 v[88:91], v216, s[56:57] offset:96
	global_load_dwordx4 v[92:95], v216, s[56:57] offset:112
	s_waitcnt vmcnt(8) lgkmcnt(0)
	s_barrier
	ds_bpermute_b32 v252, v180, v220
	s_waitcnt lgkmcnt(0)
	v_add_f32_e32 v220, v220, v252
	ds_bpermute_b32 v252, v181, v220
	s_waitcnt lgkmcnt(0)
	v_add_f32_e32 v220, v220, v252
	ds_bpermute_b32 v252, v180, v221
	s_waitcnt lgkmcnt(0)
	v_add_f32_e32 v221, v221, v252
	ds_bpermute_b32 v252, v181, v221
	s_waitcnt lgkmcnt(0)
	v_add_f32_e32 v221, v221, v252
	v_rcp_f32_e32 v248, v220
	v_rcp_f32_e32 v249, v221
	s_nop 0
	v_fma_f32 v252, -v220, v248, 2.0
	v_mul_f32_e32 v248, v248, v252
	v_fma_f32 v252, -v221, v249, 2.0
	v_mul_f32_e32 v249, v249, v252
	v_add_u32_e32 v252, s68, v250
	v_lshlrev_b32_e32 v252, 9, v252
	v_lshrrev_b32_e32 v253, 2, v250
	v_lshl_add_u32 v252, v253, 6, v252
	v_and_b32_e32 v253, 3, v250
	v_xor_b32_e32 v253, v253, v251
	v_lshl_add_u32 v252, v253, 4, v252
	s_lshl_b32 s17, s69, 10
	s_add_i32 s17, s17, 0x200
	v_add_u32_e32 v252, s17, v252
	v_add_u32_e32 v253, 0x2100, v252
	v_mul_f32_e32 v0, v0, v248
	v_mul_f32_e32 v1, v1, v248
	v_mul_f32_e32 v2, v2, v248
	v_mul_f32_e32 v3, v3, v248
	ds_write_b128 v252, v[0:3]
	v_mul_f32_e32 v8, v8, v248
	v_mul_f32_e32 v9, v9, v248
	v_mul_f32_e32 v10, v10, v248
	v_mul_f32_e32 v11, v11, v248
	v_xor_b32_e32 v222, 64, v252
	ds_write_b128 v222, v[8:11]
	v_mul_f32_e32 v16, v16, v248
	v_mul_f32_e32 v17, v17, v248
	v_mul_f32_e32 v18, v18, v248
	v_mul_f32_e32 v19, v19, v248
	v_xor_b32_e32 v222, 128, v252
	ds_write_b128 v222, v[16:19]
	v_mul_f32_e32 v24, v24, v248
	v_mul_f32_e32 v25, v25, v248
	v_mul_f32_e32 v26, v26, v248
	v_mul_f32_e32 v27, v27, v248
	v_xor_b32_e32 v222, 192, v252
	ds_write_b128 v222, v[24:27]
	v_mul_f32_e32 v32, v32, v248
	v_mul_f32_e32 v33, v33, v248
	v_mul_f32_e32 v34, v34, v248
	v_mul_f32_e32 v35, v35, v248
	v_xor_b32_e32 v222, 256, v252
	ds_write_b128 v222, v[32:35]
	v_mul_f32_e32 v40, v40, v248
	v_mul_f32_e32 v41, v41, v248
	v_mul_f32_e32 v42, v42, v248
	v_mul_f32_e32 v43, v43, v248
	v_xor_b32_e32 v222, 320, v252
	ds_write_b128 v222, v[40:43]
	v_mul_f32_e32 v48, v48, v248
	v_mul_f32_e32 v49, v49, v248
	v_mul_f32_e32 v50, v50, v248
	v_mul_f32_e32 v51, v51, v248
	v_xor_b32_e32 v222, 384, v252
	ds_write_b128 v222, v[48:51]
	v_mul_f32_e32 v56, v56, v248
	v_mul_f32_e32 v57, v57, v248
	v_mul_f32_e32 v58, v58, v248
	v_mul_f32_e32 v59, v59, v248
	v_xor_b32_e32 v222, 448, v252
	ds_write_b128 v222, v[56:59]
	v_mul_f32_e32 v4, v4, v249
	v_mul_f32_e32 v5, v5, v249
	v_mul_f32_e32 v6, v6, v249
	v_mul_f32_e32 v7, v7, v249
	ds_write_b128 v253, v[4:7]
	v_mul_f32_e32 v12, v12, v249
	v_mul_f32_e32 v13, v13, v249
	v_mul_f32_e32 v14, v14, v249
	v_mul_f32_e32 v15, v15, v249
	v_xor_b32_e32 v222, 64, v253
	ds_write_b128 v222, v[12:15]
	v_mul_f32_e32 v20, v20, v249
	v_mul_f32_e32 v21, v21, v249
	v_mul_f32_e32 v22, v22, v249
	v_mul_f32_e32 v23, v23, v249
	v_xor_b32_e32 v222, 128, v253
	ds_write_b128 v222, v[20:23]
	v_mul_f32_e32 v28, v28, v249
	v_mul_f32_e32 v29, v29, v249
	v_mul_f32_e32 v30, v30, v249
	v_mul_f32_e32 v31, v31, v249
	v_xor_b32_e32 v222, 192, v253
	ds_write_b128 v222, v[28:31]
	v_mul_f32_e32 v36, v36, v249
	v_mul_f32_e32 v37, v37, v249
	v_mul_f32_e32 v38, v38, v249
	v_mul_f32_e32 v39, v39, v249
	v_xor_b32_e32 v222, 256, v253
	ds_write_b128 v222, v[36:39]
	v_mul_f32_e32 v44, v44, v249
	v_mul_f32_e32 v45, v45, v249
	v_mul_f32_e32 v46, v46, v249
	v_mul_f32_e32 v47, v47, v249
	v_xor_b32_e32 v222, 320, v253
	ds_write_b128 v222, v[44:47]
	v_mul_f32_e32 v52, v52, v249
	v_mul_f32_e32 v53, v53, v249
	v_mul_f32_e32 v54, v54, v249
	v_mul_f32_e32 v55, v55, v249
	v_xor_b32_e32 v222, 384, v253
	ds_write_b128 v222, v[52:55]
	v_mul_f32_e32 v60, v60, v249
	v_mul_f32_e32 v61, v61, v249
	v_mul_f32_e32 v62, v62, v249
	v_mul_f32_e32 v63, v63, v249
	v_xor_b32_e32 v222, 448, v253
	ds_write_b128 v222, v[60:63]
	s_waitcnt lgkmcnt(0)
	s_barrier
	v_and_b32_e32 v128, 31, v213
	v_lshrrev_b32_e32 v129, 3, v160
	v_xor_b32_e32 v128, v128, v129
	v_lshlrev_b32_e32 v128, 4, v128
	v_lshl_add_u32 v128, v213, 9, v128
	v_add_u32_e32 v128, 0x200, v128
	v_add_u32_e32 v129, 0x10000, v128
	ds_read_b128 v[0:3], v128
	ds_read_b128 v[32:35], v129
	v_xor_b32_e32 v130, 16, v128
	v_xor_b32_e32 v131, 16, v129
	ds_read_b128 v[4:7], v130
	ds_read_b128 v[36:39], v131
	v_xor_b32_e32 v130, 32, v128
	v_xor_b32_e32 v131, 32, v129
	ds_read_b128 v[8:11], v130
	ds_read_b128 v[40:43], v131
	v_xor_b32_e32 v130, 48, v128
	v_xor_b32_e32 v131, 48, v129
	ds_read_b128 v[12:15], v130
	ds_read_b128 v[44:47], v131
	v_xor_b32_e32 v130, 64, v128
	v_xor_b32_e32 v131, 64, v129
	ds_read_b128 v[16:19], v130
	ds_read_b128 v[48:51], v131
	v_xor_b32_e32 v130, 80, v128
	v_xor_b32_e32 v131, 80, v129
	ds_read_b128 v[20:23], v130
	ds_read_b128 v[52:55], v131
	v_xor_b32_e32 v130, 96, v128
	v_xor_b32_e32 v131, 96, v129
	ds_read_b128 v[24:27], v130
	ds_read_b128 v[56:59], v131
	v_xor_b32_e32 v130, 112, v128
	v_xor_b32_e32 v131, 112, v129
	ds_read_b128 v[28:31], v130
	ds_read_b128 v[60:63], v131
	v_add_u32_e32 v132, s40, v213
	v_ashrrev_i32_e32 v133, 31, v132
	v_lshlrev_b64 v[132:133], 11, v[132:133]
	v_lshl_add_u64 v[132:133], s[42:43], 0, v[132:133]
	s_lshl_b32 s40, s97, 1
	v_lshl_add_u64 v[132:133], v[132:133], 0, s[40:41]
	v_lshl_add_u64 v[132:133], v[132:133], 0, v[160:161]
	s_mov_b64 s[18:19], 0x5000400
	v_lshl_add_u64 v[132:133], v[132:133], 0, s[18:19]
	s_waitcnt lgkmcnt(0)
	v_mov_b32_e32 v131, 0
	v_fma_f32 v0, -v170, v32, v0
	v_fma_f32 v1, -v170, v33, v1
	v_fma_f32 v2, -v170, v34, v2
	v_fma_f32 v3, -v170, v35, v3
	v_fma_f32 v4, -v170, v36, v4
	v_fma_f32 v5, -v170, v37, v5
	v_fma_f32 v6, -v170, v38, v6
	v_fma_f32 v7, -v170, v39, v7
	v_fma_f32 v8, -v170, v40, v8
	v_fma_f32 v9, -v170, v41, v9
	v_fma_f32 v10, -v170, v42, v10
	v_fma_f32 v11, -v170, v43, v11
	v_fma_f32 v12, -v170, v44, v12
	v_fma_f32 v13, -v170, v45, v13
	v_fma_f32 v14, -v170, v46, v14
	v_fma_f32 v15, -v170, v47, v15
	v_fma_f32 v16, -v170, v48, v16
	v_fma_f32 v17, -v170, v49, v17
	v_fma_f32 v18, -v170, v50, v18
	v_fma_f32 v19, -v170, v51, v19
	v_fma_f32 v20, -v170, v52, v20
	v_fma_f32 v21, -v170, v53, v21
	v_fma_f32 v22, -v170, v54, v22
	v_fma_f32 v23, -v170, v55, v23
	v_fma_f32 v24, -v170, v56, v24
	v_fma_f32 v25, -v170, v57, v25
	v_fma_f32 v26, -v170, v58, v26
	v_fma_f32 v27, -v170, v59, v27
	v_fma_f32 v28, -v170, v60, v28
	v_fma_f32 v29, -v170, v61, v29
	v_fma_f32 v30, -v170, v62, v30
	v_fma_f32 v31, -v170, v63, v31
	v_fmac_f32_e32 v131, v0, v0
	v_fmac_f32_e32 v131, v1, v1
	v_fmac_f32_e32 v131, v2, v2
	v_fmac_f32_e32 v131, v3, v3
	v_fmac_f32_e32 v131, v4, v4
	v_fmac_f32_e32 v131, v5, v5
	v_fmac_f32_e32 v131, v6, v6
	v_fmac_f32_e32 v131, v7, v7
	v_fmac_f32_e32 v131, v8, v8
	v_fmac_f32_e32 v131, v9, v9
	v_fmac_f32_e32 v131, v10, v10
	v_fmac_f32_e32 v131, v11, v11
	v_fmac_f32_e32 v131, v12, v12
	v_fmac_f32_e32 v131, v13, v13
	v_fmac_f32_e32 v131, v14, v14
	v_fmac_f32_e32 v131, v15, v15
	v_fmac_f32_e32 v131, v16, v16
	v_fmac_f32_e32 v131, v17, v17
	v_fmac_f32_e32 v131, v18, v18
	v_fmac_f32_e32 v131, v19, v19
	v_fmac_f32_e32 v131, v20, v20
	v_fmac_f32_e32 v131, v21, v21
	v_fmac_f32_e32 v131, v22, v22
	v_fmac_f32_e32 v131, v23, v23
	v_fmac_f32_e32 v131, v24, v24
	v_fmac_f32_e32 v131, v25, v25
	v_fmac_f32_e32 v131, v26, v26
	v_fmac_f32_e32 v131, v27, v27
	v_fmac_f32_e32 v131, v28, v28
	v_fmac_f32_e32 v131, v29, v29
	v_fmac_f32_e32 v131, v30, v30
	v_fmac_f32_e32 v131, v31, v31
	s_nop 1
	v_add_f32_dpp v131, v131, v131 quad_perm:[1,0,3,2] row_mask:0xf bank_mask:0xf bound_ctrl:1
	s_nop 1
	v_add_f32_dpp v131, v131, v131 quad_perm:[2,3,0,1] row_mask:0xf bank_mask:0xf bound_ctrl:1
	v_mov_b32_e32 v134, 0x358637bd
	v_fmac_f32_e32 v134, 0x3c000000, v131
	v_rsq_f32_e32 v135, v134
	s_nop 0
	v_mul_f32_e32 v136, v134, v135
	v_mul_f32_e32 v136, v136, v135
	v_mov_b32_e32 v137, 0x3fc00000
	v_fma_f32 v136, v136, -0.5, v137
	v_mul_f32_e32 v135, v135, v136
	v_mul_f32_e32 v135, v135, v200
	s_waitcnt vmcnt(0)
	v_mul_f32_e32 v0, v0, v135
	v_mul_f32_e32 v1, v1, v135
	v_mul_f32_e32 v2, v2, v135
	v_mul_f32_e32 v3, v3, v135
	v_mul_f32_e32 v4, v4, v135
	v_mul_f32_e32 v5, v5, v135
	v_mul_f32_e32 v6, v6, v135
	v_mul_f32_e32 v7, v7, v135
	v_mul_f32_e32 v8, v8, v135
	v_mul_f32_e32 v9, v9, v135
	v_mul_f32_e32 v10, v10, v135
	v_mul_f32_e32 v11, v11, v135
	v_mul_f32_e32 v12, v12, v135
	v_mul_f32_e32 v13, v13, v135
	v_mul_f32_e32 v14, v14, v135
	v_mul_f32_e32 v15, v15, v135
	v_mul_f32_e32 v16, v16, v135
	v_mul_f32_e32 v17, v17, v135
	v_mul_f32_e32 v18, v18, v135
	v_mul_f32_e32 v19, v19, v135
	v_mul_f32_e32 v20, v20, v135
	v_mul_f32_e32 v21, v21, v135
	v_mul_f32_e32 v22, v22, v135
	v_mul_f32_e32 v23, v23, v135
	v_mul_f32_e32 v24, v24, v135
	v_mul_f32_e32 v25, v25, v135
	v_mul_f32_e32 v26, v26, v135
	v_mul_f32_e32 v27, v27, v135
	v_mul_f32_e32 v28, v28, v135
	v_mul_f32_e32 v29, v29, v135
	v_mul_f32_e32 v30, v30, v135
	v_mul_f32_e32 v31, v31, v135
	v_mul_f32_e32 v0, v0, v64
	v_mul_f32_e32 v1, v1, v65
	v_mul_f32_e32 v2, v2, v66
	v_mul_f32_e32 v3, v3, v67
	v_mul_f32_e32 v4, v4, v68
	v_mul_f32_e32 v5, v5, v69
	v_mul_f32_e32 v6, v6, v70
	v_mul_f32_e32 v7, v7, v71
	v_mul_f32_e32 v8, v8, v72
	v_mul_f32_e32 v9, v9, v73
	v_mul_f32_e32 v10, v10, v74
	v_mul_f32_e32 v11, v11, v75
	v_mul_f32_e32 v12, v12, v76
	v_mul_f32_e32 v13, v13, v77
	v_mul_f32_e32 v14, v14, v78
	v_mul_f32_e32 v15, v15, v79
	v_mul_f32_e32 v16, v16, v80
	v_mul_f32_e32 v17, v17, v81
	v_mul_f32_e32 v18, v18, v82
	v_mul_f32_e32 v19, v19, v83
	v_mul_f32_e32 v20, v20, v84
	v_mul_f32_e32 v21, v21, v85
	v_mul_f32_e32 v22, v22, v86
	v_mul_f32_e32 v23, v23, v87
	v_mul_f32_e32 v24, v24, v88
	v_mul_f32_e32 v25, v25, v89
	v_mul_f32_e32 v26, v26, v90
	v_mul_f32_e32 v27, v27, v91
	v_mul_f32_e32 v28, v28, v92
	v_mul_f32_e32 v29, v29, v93
	v_mul_f32_e32 v30, v30, v94
	v_mul_f32_e32 v31, v31, v95
	v_cvt_pk_bf16_f32 v96, v0, v1
	v_cvt_pk_bf16_f32 v97, v2, v3
	v_cvt_pk_bf16_f32 v98, v4, v5
	v_cvt_pk_bf16_f32 v99, v6, v7
	v_cvt_pk_bf16_f32 v100, v8, v9
	v_cvt_pk_bf16_f32 v101, v10, v11
	v_cvt_pk_bf16_f32 v102, v12, v13
	v_cvt_pk_bf16_f32 v103, v14, v15
	v_cvt_pk_bf16_f32 v104, v16, v17
	v_cvt_pk_bf16_f32 v105, v18, v19
	v_cvt_pk_bf16_f32 v106, v20, v21
	v_cvt_pk_bf16_f32 v107, v22, v23
	v_cvt_pk_bf16_f32 v108, v24, v25
	v_cvt_pk_bf16_f32 v109, v26, v27
	v_cvt_pk_bf16_f32 v110, v28, v29
	v_cvt_pk_bf16_f32 v111, v30, v31
	global_store_dwordx4 v[132:133], v[96:99], off
	global_store_dwordx4 v[132:133], v[100:103], off offset:16
	global_store_dwordx4 v[132:133], v[104:107], off offset:32
	global_store_dwordx4 v[132:133], v[108:111], off offset:48
	s_barrier
	s_add_i32 s96, s96, s34
	s_cmpk_lt_i32 s96, 0x200
	s_cbranch_scc1 .LBB0_401
	s_branch .LBB0_422
